# LoRA waves keep their 8 B fragments resident in v220-v251 (loaded once before the scan loop) instead of 8 global loads with exposed round trips per chunk
# speedup vs baseline: 1.0186x; 1.0090x over previous
; __device__ __forceinline__ uint2 pack4(f32x4 v) { uint2 u; u.x = cvt_pk_bf16(v[0], v[1]); u.y = cvt_pk_bf16(v[2], v[3]); return u; }
; #define MFMA16(a, b, c) __builtin_amdgcn_mfma_f32_16x16x32_bf16(a, b, c, 0, 0, 0)
; __device__ __forceinline__ void scan_phase(PREF p, char* smem, const int wid_u) {
;     ...
;     for (int c = 0; c < nch; ++c) {
;       {
;         const int mat = wave >> 1, mts = wave & 1;
;         const bf16_t* As = (mat & 1) ? Kt : Bt;
;         const bf16_t* Bs = (mat & 2) ? Rt : At;
;         f32x4 acc[2] = {};
; #pragma unroll
;         for (int ks = 0; ks < 2; ++ks) {
;           const bf16x8 a = ldfrag(As, 72, mts * 16, ks * 32, fr, fq);
; #pragma unroll
;           for (int nt = 0; nt < 2; ++nt) acc[nt] = MFMA16(a, ldfrag(Bs, 72, nt * 16, ks * 32, fr, fq), acc[nt]);
;         }
; #pragma unroll
;         for (int nt = 0; nt < 2; ++nt) {
;           const int tcol = nt * 16 + fr;
;           f32x4 v = acc[nt];
; #pragma unroll
;           for (int jj = 0; jj < 4; ++jj) {
;             const int srow = mts * 16 + fq * 4 + jj;
;             const bool keep = (mat & 2) ? (srow <= tcol) : (srow < tcol);
;             v[jj] = keep ? v[jj] : 0.f;
;           }
;           if (mat == 0) {
; #pragma unroll
;             for (int jj = 0; jj < 4; ++jj) Nab[(mts * 16 + fq * 4 + jj) * 32 + tcol] = v[jj];
;           } else {
;             bf16_t* dst = mat == 1 ? NakT : mat == 2 ? NbrT : NkrT;
;             *(uint2*)(dst + tcol * 40 + mts * 16 + fq * 4) = pack4(v);
;           }
;         }
;       }
;       lds_barrier();
;       if (wave == 4) {
;         const int irow = lane >> 1, hb = lane & 1, blk = lane >> 5, il = irow & 15;
;         float x[8];
; #pragma unroll
;         for (int i = 0; i < 8; ++i) x[i] = (hb * 8 + i == il) ? 1.f : 0.f;
;         const float* nb = Nab + (blk * 16) * 32 + blk * 16 + hb * 8;
;         solve16<0>(x, nb);
; #pragma unroll
;         for (int i = 0; i < 8; ++i) TT[(blk * 16 + hb * 8 + i) * 40 + blk * 16 + il] = (bf16_t)(cvt_pk_bf16(x[i], 0.f) & 0xffff);
;         if (blk == 0) *(uint4*)(T11b + il * 40 + hb * 8) = pack8(x);
.LBB0_537:
	s_lshr_b32 s44, s92, 5
	s_mul_i32 s18, s26, 0x6000000
	s_add_u32 s18, s48, s18
	s_addc_u32 s19, s49, 0
	s_add_u32 s64, s18, 0xee90000
	s_addc_u32 s65, s19, 0
	s_cmp_eq_u32 s20, 0
	s_mov_b32 s18, 0xe400
	v_lshlrev_b32_e32 v80, 2, v79
	s_cselect_b32 s18, s18, 0xf600
	v_or_b32_e32 v48, s84, v80
	s_add_i32 s20, s18, 0
	s_and_b32 s18, s90, 4
	s_add_i32 s28, 0, 0xc000
	s_add_i32 s29, 0, 0xd200
	v_cmp_lt_u32_e32 vcc, v48, v77
	s_cmp_eq_u32 s18, 0
	v_mul_u32_u24_e32 v128, 0x90, v90
	v_cndmask_b32_e64 v49, 0, 1, vcc
	v_cmp_le_u32_e32 vcc, v48, v77
	v_mul_u32_u24_e32 v69, 40, v77
	v_add_u32_e32 v138, s27, v55
	v_cndmask_b32_e64 v50, 0, 1, vcc
	s_cselect_b64 vcc, -1, 0
	v_cndmask_b32_e32 v49, v50, v49, vcc
	s_and_b64 s[18:19], vcc, exec
	v_lshlrev_b32_e32 v50, 1, v78
	s_cselect_b32 s18, s28, s29
	v_add3_u32 v129, s20, v128, v50
	s_add_i32 s20, 0, 0x2a00
	s_add_i32 s28, 0, 0x2000
	v_add_u32_e32 v51, s18, v50
	s_and_b64 s[18:19], s[22:23], exec
	s_cselect_b32 s18, s28, s20
	s_add_i32 s19, 0, 0x1000
	s_cmp_eq_u32 s25, 1
	s_cselect_b32 s18, s19, s18
	s_lshl_b32 s19, s84, 1
	s_add_i32 s18, s18, s19
	v_add_u32_e32 v52, s18, v78
	s_add_i32 s18, 0, 0x13000
	v_add_u32_e32 v131, s18, v50
	s_add_i32 s18, 0, 0x25100
	v_add_u32_e32 v53, s18, v55
	s_add_i32 s18, 0, 0x1f100
	v_add_u32_e32 v56, s18, v55
	s_add_i32 s18, 0, 0x10800
	s_add_i32 s20, 0, 0x1d100
	s_add_i32 s34, 0, 0x21100
	s_add_i32 s35, 0, 0x14400
	s_add_i32 s36, s19, 0
	v_add_u32_e32 v57, s18, v50
	s_add_i32 s18, 0, 0x11c00
	s_and_b32 s28, s90, -2
	s_cmp_eq_u32 s28, 2
	s_cselect_b64 s[28:29], -1, 0
	s_cmp_gt_i32 s90, 5
	s_cselect_b64 s[30:31], -1, 0
	s_or_b64 s[66:67], s[30:31], s[28:29]
	s_cmp_lt_u32 s90, 4
	s_cselect_b32 s28, -2, -4
	v_add3_u32 v139, s20, v55, v54
	s_add_i32 s20, 0, 0x27500
	v_add_u32_e32 v141, s20, v55
	s_add_i32 s20, 0, 0x27900
	v_add_u32_e32 v142, s20, v55
	s_add_i32 s20, 0, 0x27400
	v_add_u32_e32 v130, 0, v50
	s_add_i32 s28, s28, s90
	v_add_u32_e32 v143, s20, v55
	s_add_i32 s20, 0, 0x27200
	v_lshl_add_u32 v134, v69, 1, v130
	v_lshl_or_b32 v69, s28, 4, v77
	s_add_i32 s28, 0, 0x27300
	v_add_u32_e32 v144, s20, v55
	s_lshl_b32 s20, s89, 1
	s_add_u32 s27, s64, s20
	v_add_u32_e32 v137, s28, v55
	s_addc_u32 s28, s65, 0
	s_lshl_b32 s68, s25, 4
	v_add_u32_e32 v59, s21, v55
	v_lshl_add_u32 v68, v77, 7, 0
	v_mul_i32_i24_e32 v70, 0xffffffd0, v77
	v_add3_u32 v140, s34, v55, v54
	v_lshlrev_b32_e32 v55, 2, v77
	s_ashr_i32 s69, s68, 31
	v_add3_u32 v133, v68, v70, v50
	v_add_u32_e32 v70, s21, v55
	s_lshl_b64 s[20:21], s[68:69], 1
	s_add_u32 s20, s27, s20
	s_addc_u32 s21, s28, s21
	v_mov_b32_e32 v79, 0
	v_lshl_add_u64 v[82:83], s[20:21], 0, v[78:79]
	v_cmp_eq_u32_e64 s[20:21], 0, v89
	s_and_b64 s[70:71], s[20:21], s[22:23]
	s_lshl_b32 s20, s24, 3
	s_add_u32 s20, s48, s20
	s_addc_u32 s21, s49, 0
	s_lshl_b32 s22, s26, 2
	s_add_u32 s20, s20, s22
	v_mul_u32_u24_e32 v71, 40, v90
	s_movk_i32 s37, 0x50
	s_addc_u32 s21, s21, 0
	v_lshl_add_u32 v145, v71, 1, v130
	v_or_b32_e32 v71, s68, v77
	s_add_u32 s72, s20, 0x2890000
	v_mul_lo_u32 v84, v71, s37
	v_lshl_or_b32 v85, s40, 5, v77
	s_addc_u32 s73, s21, 0
	s_add_i32 s45, s92, -1
	v_add_u32_e32 v147, v130, v84
	v_add3_u32 v148, s35, v50, v84
	v_add3_u32 v149, s36, v84, v78
	v_add_u32_e32 v152, v131, v84
	v_mul_u32_u24_e32 v84, 40, v85
	v_or_b32_e32 v92, 2, v48
	v_add_u32_e32 v58, s18, v50
	s_add_u32 s74, s48, 0x3be90000
	v_lshlrev_b32_e32 v84, 1, v84
	v_cmp_lt_u32_e64 s[26:27], v92, v77
	s_addc_u32 s75, s49, 0
	s_add_i32 s22, 0, 0x16800
	v_add_u32_e32 v153, v57, v84
	v_add_u32_e32 v155, v58, v84
	v_cndmask_b32_e64 v84, 0, 1, s[26:27]
	v_cmp_le_u32_e64 s[26:27], v92, v77
	v_lshl_add_u32 v150, v85, 2, s22
	v_or_b32_e32 v86, 16, v85
	v_mul_u32_u24_e32 v157, 0x90, v85
	v_cndmask_b32_e64 v85, 0, 1, s[26:27]
	v_cndmask_b32_e32 v84, v85, v84, vcc
	v_or_b32_e32 v93, 3, v48
	v_and_b32_e32 v84, 1, v84
	v_cmp_lt_u32_e64 s[28:29], v93, v77
	v_mul_u32_u24_e32 v87, 40, v86
	v_cmp_eq_u32_e64 s[26:27], 1, v84
	v_cndmask_b32_e64 v84, 0, 1, s[28:29]
	v_cmp_le_u32_e64 s[28:29], v93, v77
	v_lshlrev_b32_e32 v87, 1, v87
	v_add_u32_e32 v156, v58, v87
	v_cndmask_b32_e64 v85, 0, 1, s[28:29]
	v_or_b32_e32 v58, 16, v77
	v_cndmask_b32_e32 v84, v85, v84, vcc
	v_and_b32_e32 v84, 1, v84
	v_cmp_lt_u32_e64 s[30:31], v48, v58
	v_add_u32_e32 v154, v57, v87
	s_lshl_b32 s20, s25, 5
	v_mul_u32_u24_e32 v57, 0x48, v90
	v_and_b32_e32 v49, 1, v49
	v_cmp_eq_u32_e64 s[28:29], 1, v84
	v_cndmask_b32_e64 v84, 0, 1, s[30:31]
	v_cmp_le_u32_e64 s[30:31], v48, v58
	s_movk_i32 s41, 0x90
	v_lshl_add_u32 v151, v86, 2, s22
	s_add_i32 s20, s20, 0
	v_lshlrev_b32_e32 v57, 1, v57
	v_lshl_add_u32 v164, v88, 2, s22
	v_cmp_eq_u32_e64 s[22:23], 1, v49
	v_or_b32_e32 v49, 1, v48
	v_cndmask_b32_e64 v85, 0, 1, s[30:31]
	v_mad_u32_u24 v60, v113, s37, 0
	v_mul_lo_u32 v136, v69, s37
	v_add3_u32 v161, s20, v57, v78
	v_mul_lo_u32 v57, v71, s41
	v_cndmask_b32_e32 v71, v48, v49, vcc
	v_cndmask_b32_e32 v84, v85, v84, vcc
	v_cmp_lt_u32_e64 s[36:37], v92, v58
	v_cmp_gt_u32_e64 s[24:25], v77, v71
	v_and_b32_e32 v84, 1, v84
	v_cmp_gt_u32_e64 s[34:35], v58, v71
	v_cndmask_b32_e64 v71, 0, 1, s[36:37]
	v_cmp_le_u32_e64 s[36:37], v92, v58
	v_cmp_eq_u32_e64 s[30:31], 1, v84
	v_cmp_lt_u32_e64 s[38:39], v93, v58
	v_cndmask_b32_e64 v84, 0, 1, s[36:37]
	v_cndmask_b32_e32 v71, v84, v71, vcc
	v_and_b32_e32 v71, 1, v71
	v_cmp_eq_u32_e64 s[36:37], 1, v71
	v_cndmask_b32_e64 v71, 0, 1, s[38:39]
	v_cmp_le_u32_e64 s[38:39], v93, v58
	v_lshrrev_b32_e32 v62, 1, v75
	v_lshlrev_b32_e32 v64, 3, v75
	v_cndmask_b32_e64 v58, 0, 1, s[38:39]
	v_cndmask_b32_e32 v58, v58, v71, vcc
	v_and_b32_e32 v58, 1, v58
	v_lshrrev_b32_e32 v63, 5, v88
	v_cmp_eq_u32_e64 s[38:39], 1, v58
	v_and_b32_e32 v58, 15, v62
	v_and_b32_e32 v62, 8, v64
	v_lshl_add_u32 v65, v63, 11, 0
	v_lshlrev_b32_e32 v66, 6, v63
	v_lshlrev_b32_e32 v64, 2, v62
	v_mul_i32_i24_e32 v67, 0xfffff820, v63
	v_add3_u32 v166, v65, v66, v64
	v_lshlrev_b32_e32 v64, 1, v58
	v_add3_u32 v64, v65, v67, v64
	v_mul_u32_u24_e32 v65, 0x50, v58
	v_lshlrev_b32_e32 v66, 1, v62
	v_add3_u32 v167, 0, v65, v66
	v_or_b32_e32 v65, 1, v62
	v_cmp_eq_u32_e32 vcc, v62, v58
	v_or_b32_e32 v66, 2, v62
	v_mul_u32_u24_e32 v159, 0x90, v86
	v_cndmask_b32_e64 v84, 0, 1.0, vcc
	v_cmp_eq_u32_e32 vcc, v58, v65
	v_or_b32_e32 v65, 3, v62
	s_add_i32 s47, 0, 0x16900
	v_cndmask_b32_e64 v85, 0, 1.0, vcc
	v_cmp_eq_u32_e32 vcc, v65, v58
	v_or_b32_e32 v65, 5, v62
	v_lshlrev_b32_e32 v61, 3, v89
	v_cndmask_b32_e64 v87, 0, 1.0, vcc
	v_cmp_eq_u32_e32 vcc, v66, v58
	v_or_b32_e32 v66, 4, v62
	s_cmp_gt_i32 s90, 4
	v_cndmask_b32_e64 v86, 0, 1.0, vcc
	v_cmp_eq_u32_e32 vcc, v65, v58
	v_or_b32_e32 v65, 7, v62
	s_waitcnt lgkmcnt(0)
	s_barrier
; __device__ __forceinline__ void scan_phase(PREF p, char* smem, const int wid_u) {
;     ...
;     uint4* Btab0 = (uint4*)(p.ws + OFF_BTAB);
;     const unsigned bti = (unsigned)(item * 1024 + (role & 1) * 512 + lane);
;     float bias[4] = {0.f, 0.f, 0.f, 0.f};
;     if (role < 2) {
;       const float* lsrc = sel(role != 0, p.a2, p.w2) + (size_t)d * 64 * 512 + h * 64;
;       if (th == 0) {
; #pragma unroll
;         for (int nt = 0; nt < 4; ++nt)
; #pragma unroll
;           for (int ks = 0; ks < 2; ++ks) {
;             float o[8];
; #pragma unroll
;             for (int q = 0; q < 8; ++q) o[q] = lsrc[(size_t)(ks * 32 + fq * 8 + q) * 512 + nt * 16 + fr];
;             Btab0[bti + (unsigned)((nt * 2 + ks) * 64)] = pack8(o);
;           }
;       }
; #pragma unroll
;       for (int nt = 0; nt < 4; ++nt) bias[nt] = sel(role != 0, p.a0, p.w0)[d * 512 + h * 64 + nt * 16 + fr];
;     }
;     const int colA = (role == 2 ? 512 : 1024) + h * 64 + cq * 16;
;     const int colB = 1536 + h * 64 + cq * 16;
;     const int alo = (role == 0 ? d * 64 : 128 + d * 64) + fq * 8;
;     Raw16 ra, rb;
;     {
;       const int j = th * 16 + tl, t = d ? T - 1 - j : j, row = r0seq + t;
;       if (role >= 2) load_raw16(ra, z, row, t, T, colA);
;       if (role == 3) load_raw16(rb, z, row, t, T, colB);
;       if (role < 2) {
;         const int j2 = th * 16 + fr, t2 = d ? T - 1 - j2 : j2;
;         const bf16_t* ap = P_ALORA + (unsigned)((r0seq + t2) * 256 + alo);
;         ra.c0 = *(const uint4*)ap; ra.c1 = *(const uint4*)(ap + 32);
;       }
;     }
;     f32x4 Sa = {0.f, 0.f, 0.f, 0.f}, Sb = Sa;
;     uint2 y_def = make_uint2(0u, 0u);
;     float sb_def = 0.f;
;     const int mt = wave >> 1, hn = wave & 1, nt0 = 2 * hn, nt1 = 2 * hn + 1;
;     asm volatile("s_waitcnt vmcnt(0)" ::: "memory");
;     __syncthreads();
;     {
;       {
;         const int j = th * 16 + tl;
;         float v16[16];
;         if (role < 2) {
;           f32x4 acc[4] = {};
;           unsigned bti_ = bti;
;           asm volatile("" : "+v"(bti_));
; #pragma unroll
;           for (int ks = 0; ks < 2; ++ks) {
;             const uint4 au = ks == 0 ? ra.c0 : ra.c1;
;             const bf16x8 a = *reinterpret_cast<const bf16x8*>(&au);
; #pragma unroll
	v_cndmask_b32_e64 v89, 0, 1.0, vcc
	v_cmp_eq_u32_e32 vcc, v66, v58
	v_cmp_gt_u32_e64 s[18:19], 32, v88
	v_add3_u32 v158, s20, v157, v78
	v_add3_u32 v160, s20, v159, v78
	v_add3_u32 v162, s47, v57, v50
	v_or_b32_e32 v50, s68, v80
	s_cselect_b64 s[20:21], -1, 0
	v_lshl_or_b32 v63, v63, 4, v62
	v_cndmask_b32_e64 v88, 0, 1.0, vcc
	v_or_b32_e32 v62, 6, v62
	v_cmp_eq_u32_e32 vcc, v65, v58
	s_lshl_b32 s40, s40, 6
	v_lshl_add_u32 v132, v78, 2, v68
	v_sub_u32_e32 v68, 0, v78
	v_add_u32_e32 v69, 0, v136
	v_mul_u32_u24_e32 v57, 0x90, v77
	v_mul_u32_u24_e32 v165, 0x50, v77
	v_add_u32_e32 v55, 0, v55
	v_lshlrev_b32_e32 v94, 7, v48
	v_lshlrev_b32_e32 v95, 7, v49
	v_lshlrev_b32_e32 v96, 7, v92
	v_lshlrev_b32_e32 v97, 7, v93
	v_cndmask_b32_e64 v91, 0, 1.0, vcc
	v_cmp_eq_u32_e32 vcc, v62, v58
	v_mul_u32_u24_e32 v58, 0x50, v63
	v_lshlrev_b32_e32 v48, 8, v48
	v_lshlrev_b32_e32 v49, 8, v49
	v_lshlrev_b32_e32 v62, 8, v92
	v_lshlrev_b32_e32 v63, 8, v93
	s_add_i32 s47, s47, s40
	v_lshlrev_b32_e32 v65, 1, v77
	v_mul_lo_u32 v50, v50, s41
	s_movk_i32 s76, 0xec00
	v_sub_u32_e32 v135, v133, v78
	v_add_u32_e32 v163, 0xffffff00, v115
	v_cndmask_b32_e64 v90, 0, 1.0, vcc
	s_lshl_b32 s46, s90, 12
	v_add3_u32 v168, s47, v65, v50
	s_sub_i32 s47, 0, s84
	v_sub_u32_e32 v169, s92, v77
	v_sub_u32_e32 v170, s92, v113
	s_sub_i32 s87, 0, s44
	v_add_u32_e32 v171, v51, v57
	v_add_u32_e32 v172, v60, v61
	v_add_u32_e32 v173, v69, v78
	v_add_u32_e32 v174, v64, v58
	v_add_u32_e32 v175, v133, v68
	v_mov_b32_e32 v176, 0x260
	v_add_u32_e32 v177, v53, v54
	v_add_u32_e32 v178, v56, v54
	s_movk_i32 s88, 0xa00
	s_mov_b32 s77, -1
	s_mov_b64 s[78:79], 0x1400
	v_add_u32_e32 v179, v59, v54
	v_add_u32_e32 v180, v52, v165
	v_add_u32_e32 v181, v55, v94
	v_add_u32_e32 v182, v55, v95
	v_add_u32_e32 v183, v55, v96
	v_add_u32_e32 v184, v55, v97
	v_add_u32_e32 v185, v70, v48
	v_add_u32_e32 v186, v70, v49
	v_add_u32_e32 v187, v70, v62
	v_add_u32_e32 v188, v70, v63
	s_mov_b32 s93, s84
	v_mov_b32_e32 v48, v79
	v_mov_b32_e32 v49, v79
	v_mov_b32_e32 v50, v79
	v_mov_b32_e32 v51, v79
	v_mov_b32_e32 v52, v79
	v_mov_b32_e32 v53, v79
	v_mov_b32_e32 v54, v79
	v_mov_b32_e32 v55, v79
	v_mov_b32_e32 v92, v79
	v_mov_b32_e32 v93, v79
	s_load_dwordx2 s[100:101], s[0:1], 0x110
	s_lshr_b32 s98, s33, 4
	s_lshl_b32 s98, s98, 8
	s_and_b32 s99, s33, 15
	s_lshl_b32 s99, s99, 2
	s_add_u32 s98, s98, s99
	s_add_u32 s98, s98, 0x3ee90440
	s_waitcnt lgkmcnt(0)
	s_add_u32 s100, s100, s98
	s_addc_u32 s101, s101, 0
	s_cmp_gt_u32 s90, 3
	s_cbranch_scc1 .Lbt_skip
	v_mov_b32_e32 v56, v72
	v_mov_b32_e32 v57, 0
	v_lshl_add_u64 v[56:57], v[56:57], 4, s[54:55]
	s_mov_b64 s[98:99], 0x1000
	v_lshl_add_u64 v[60:61], v[56:57], 0, s[98:99]
	global_load_dwordx4 v[220:223], v[56:57], off
	global_load_dwordx4 v[224:227], v[56:57], off offset:1024
	global_load_dwordx4 v[228:231], v[56:57], off offset:2048
	global_load_dwordx4 v[232:235], v[56:57], off offset:3072
	global_load_dwordx4 v[236:239], v[60:61], off
	global_load_dwordx4 v[240:243], v[60:61], off offset:1024
	global_load_dwordx4 v[244:247], v[60:61], off offset:2048
	global_load_dwordx4 v[248:251], v[60:61], off offset:3072
	s_waitcnt vmcnt(0)
.Lbt_skip:
	s_branch .LBB0_540
; __device__ __forceinline__ float quad_sum(float x) { x += dpp_f<0xB1>(x); x += dpp_f<0x4E>(x); return x; }
; __device__ __forceinline__ void scan_phase(PREF p, char* smem, const int wid_u) {
;     ...
;         const int k = lane, seg = wave;
;         const float* sw = stepbuf + 0 * SV + k;
;         const float P15 = sw[15 * 64];
;         const float hiF = seg >= 4 ? P15 : 1.f;
;         float P[5];
;         P[0] = seg == 0 ? 1.f : sw[(4 * seg - 1) * 64] * (seg > 4 ? P15 : 1.f);
; #pragma unroll
;         for (int i = 0; i < 4; ++i) P[i + 1] = sw[(4 * seg + i) * 64] * hiF;
;         const float PL = sw[31 * 64] * P15;
;         if (role == 2) {
;           const int j = th * 16 + tl;
;           float bs = 0.f;
; #pragma unroll
;           for (int q = 0; q < 16; ++q) {
;             const float kd_ = stepbuf[1 * SV + j * 64 + cq * 16 + q] * (1.f + (stepbuf[4 * SV + j * 64 + cq * 16 + q] - 1.f) * cst[6 * 64 + cq * 16 + q]);
;             bs += stepbuf[2 * SV + j * 64 + cq * 16 + q] * kd_ * cst[7 * 64 + cq * 16 + q];
;           }
;           bs = quad_sum(bs);
;           sb_def = bs;
;         }
;         f32x4 bb, kb, at, vv;
; #pragma unroll
;         for (int i = 0; i < 4; ++i) {
;           const int t = 4 * seg + i;
;           const float inv = __builtin_amdgcn_rcpf(P[i + 1]);
;           const float nav = stepbuf[3 * SV + t * 64 + k], av = stepbuf[4 * SV + t * 64 + k];
;           const float a_ = P[i] * nav;
;           const float rraw = stepbuf[2 * SV + t * 64 + k];
;           const float kraw = stepbuf[1 * SV + t * 64 + k] * (1.f + (av - 1.f) * cst[6 * 64 + k]);
;           const float r_ = P[i + 1] * rraw;
;           const float b_ = -nav * av * inv;
;           const float k_ = kraw * inv;
;           At[t * 72 + k] = (bf16_t)(cvt_pk_bf16(a_, 0.f) & 0xffff);
;           Rt[t * 72 + k] = (bf16_t)(cvt_pk_bf16(r_, 0.f) & 0xffff);
;           Bt[t * 72 + k] = (bf16_t)(cvt_pk_bf16(b_, 0.f) & 0xffff);
;           Kt[t * 72 + k] = (bf16_t)(cvt_pk_bf16(k_, 0.f) & 0xffff);
;           bb[i] = b_ * PL; kb[i] = k_ * PL; at[i] = a_;
;           vv[i] = stepbuf[5 * SV + t * 64 + k];
;         }
;         *(uint2*)(Bb + k * 40 + 4 * seg) = pack4(bb);
;         *(uint2*)(Kb + k * 40 + 4 * seg) = pack4(kb);
;         *(uint2*)(VT + k * 40 + 4 * seg) = pack4(vv);
;         *(uint2*)(AtTb + k * 40 + 4 * seg) = pack4(at);
;         if (seg == 0) PLs[k] = PL;
.LBB0_538:
	s_waitcnt lgkmcnt(5)
	v_cndmask_b32_e64 v68, 1.0, v64, s[14:15]
	ds_read2st64_b32 v[92:93], v116 offset0:32 offset1:64
	s_waitcnt lgkmcnt(5)
	v_mul_f32_e32 v61, v68, v61
	s_waitcnt lgkmcnt(3)
	v_pk_mul_f32 v[70:71], v[68:69], v[62:63] op_sel_hi:[0,1]
	s_waitcnt lgkmcnt(2)
	v_mul_f32_e32 v63, v68, v65
	s_waitcnt lgkmcnt(1)
	v_mul_f32_e32 v62, v64, v66
	ds_read2st64_b32 v[66:67], v116 offset0:96 offset1:128
	ds_read2st64_b32 v[68:69], v119 offset0:96 offset1:128
	ds_read2st64_b32 v[96:97], v119 offset0:32 offset1:64
	s_waitcnt lgkmcnt(3)
	v_mul_f32_e32 v65, v61, v93
	v_cvt_pk_bf16_f32 v65, v65, s0
	s_waitcnt lgkmcnt(2)
	v_mov_b32_e32 v94, v66
	s_waitcnt lgkmcnt(1)
	v_mov_b32_e32 v95, v68
	v_rcp_f32_e32 v64, v61
	ds_write_b16 v118, v65 offset:53760
	v_rcp_f32_e32 v65, v70
	v_pk_mul_f32 v[60:61], v[60:61], v[94:95]
	v_mov_b32_e32 v68, v67
	v_cvt_pk_bf16_f32 v66, v60, s0
	ds_write_b16 v118, v66 offset:49152
	s_waitcnt lgkmcnt(2)
	v_mul_f32_e32 v66, v70, v97
	v_cvt_pk_bf16_f32 v97, v66, s0
	v_pk_mul_f32 v[66:67], v[68:69], v[94:95] neg_lo:[0,1] neg_hi:[0,1]
	v_cvt_pk_bf16_f32 v78, v61, s0
	v_pk_mul_f32 v[66:67], v[64:65], v[66:67]
	v_cvt_pk_bf16_f32 v60, v60, v61
	v_cvt_pk_bf16_f32 v93, v66, s0
	ds_write_b16 v118, v93 offset:58368
	v_pk_mul_f32 v[94:95], v[62:63], v[66:67] op_sel_hi:[0,1]
	v_cvt_pk_bf16_f32 v98, v67, s0
	v_pk_add_f32 v[66:67], v[68:69], -1.0 op_sel_hi:[1,0]
	ds_read_b32 v68, v117 offset:1536
	ds_read_b32 v104, v116 offset:40960
	ds_read_b32 v105, v119 offset:40960
	ds_read_b32 v106, v121 offset:40960
	ds_read_b32 v107, v122 offset:40960
	s_waitcnt lgkmcnt(4)
	v_pk_fma_f32 v[66:67], v[68:69], v[66:67], 1.0 op_sel_hi:[0,1,0]
	v_mov_b32_e32 v93, v96
	v_pk_mul_f32 v[66:67], v[92:93], v[66:67]
	s_and_b64 vcc, exec, s[16:17]
	v_pk_mul_f32 v[64:65], v[64:65], v[66:67]
	s_nop 0
	v_cvt_pk_bf16_f32 v66, v64, s0
	ds_write_b16 v118, v66 offset:62976
	ds_write_b16 v120, v78 offset:49152
	ds_write_b16 v120, v97 offset:53760
	ds_write_b16 v120, v98 offset:58368
	ds_read2st64_b32 v[92:93], v121 offset0:32 offset1:64
	ds_read2st64_b32 v[96:97], v121 offset0:96 offset1:128
	ds_read2st64_b32 v[98:99], v122 offset0:96 offset1:128
	v_pk_mul_f32 v[66:67], v[62:63], v[64:65] op_sel_hi:[0,1]
	v_cvt_pk_bf16_f32 v64, v65, s0
	s_waitcnt lgkmcnt(2)
	v_mul_f32_e32 v65, v71, v93
	ds_read2st64_b32 v[102:103], v122 offset0:32 offset1:64
	v_cvt_pk_bf16_f32 v65, v65, s0
	ds_write_b16 v120, v64 offset:62976
	v_rcp_f32_e32 v64, v71
	ds_write_b16 v120, v65 offset:53904
	v_rcp_f32_e32 v65, v63
	s_waitcnt lgkmcnt(4)
	v_mov_b32_e32 v100, v96
	s_waitcnt lgkmcnt(3)
	v_mov_b32_e32 v101, v98
	v_mov_b32_e32 v98, v97
	v_pk_mul_f32 v[70:71], v[70:71], v[100:101]
	s_waitcnt lgkmcnt(2)
	v_mul_f32_e32 v63, v63, v103
	v_pk_mul_f32 v[96:97], v[98:99], v[100:101] neg_lo:[0,1] neg_hi:[0,1]
	v_cvt_pk_bf16_f32 v69, v70, s0
	v_cvt_pk_bf16_f32 v63, v63, s0
	v_pk_mul_f32 v[96:97], v[64:65], v[96:97]
	ds_write_b16 v120, v69 offset:49296
	v_cvt_pk_bf16_f32 v69, v96, s0
	v_pk_mul_f32 v[100:101], v[62:63], v[96:97] op_sel_hi:[0,1]
	v_cvt_pk_bf16_f32 v103, v97, s0
	v_pk_add_f32 v[96:97], v[98:99], -1.0 op_sel_hi:[1,0]
	ds_write_b16 v120, v69 offset:58512
	v_pk_fma_f32 v[68:69], v[68:69], v[96:97], 1.0 op_sel_hi:[0,1,0]
	v_mov_b32_e32 v93, v102
	v_pk_mul_f32 v[68:69], v[92:93], v[68:69]
	v_cvt_pk_bf16_f32 v78, v71, s0
	v_pk_mul_f32 v[64:65], v[64:65], v[68:69]
	v_cvt_pk_bf16_f32 v61, v70, v71
	v_cvt_pk_bf16_f32 v68, v64, s0
	ds_write_b16 v120, v68 offset:63120
	v_pk_mul_f32 v[68:69], v[62:63], v[64:65] op_sel_hi:[0,1]
	ds_write_b16 v120, v78 offset:49440
	ds_write_b16 v120, v63 offset:54048
	ds_write_b16 v120, v103 offset:58656
	v_cvt_pk_bf16_f32 v63, v65, s0
	v_cvt_pk_bf16_f32 v64, v94, v95
	v_cvt_pk_bf16_f32 v65, v100, v101
	ds_write_b16 v120, v63 offset:63264
	ds_write_b64 v124, v[64:65]
	v_cvt_pk_bf16_f32 v64, v66, v67
	v_cvt_pk_bf16_f32 v65, v68, v69
	ds_write_b64 v125, v[64:65]
	v_cvt_pk_bf16_f32 v64, v104, v105
	v_cvt_pk_bf16_f32 v65, v106, v107
	ds_write_b64 v126, v[64:65]
	ds_write_b64 v127, v[60:61]
	s_cbranch_vccz .LBB0_602

; __device__ __forceinline__ float sigmoidf_(float x) { return __builtin_amdgcn_rcpf(1.f + __expf(-x)); }
; #define MFMA16(a, b, c) __builtin_amdgcn_mfma_f32_16x16x32_bf16(a, b, c, 0, 0, 0)
; __device__ __forceinline__ void scan_phase(PREF p, char* smem, const int wid_u) {
;     ...
;           f32x4 acc[4] = {};
;           unsigned bti_ = bti;
;           asm volatile("" : "+v"(bti_));
; #pragma unroll
;           for (int ks = 0; ks < 2; ++ks) {
;             const uint4 au = ks == 0 ? ra.c0 : ra.c1;
;             const bf16x8 a = *reinterpret_cast<const bf16x8*>(&au);
; #pragma unroll
;             for (int nt = 0; nt < 4; ++nt) { const uint4 bu = Btab0[bti_ + (unsigned)((nt * 2 + ks) * 64)]; acc[nt] = MFMA16(a, *reinterpret_cast<const bf16x8*>(&bu), acc[nt]); }
;           }
;           if (role == 0) {
; #pragma unroll
;             for (int nt = 0; nt < 4; ++nt)
; #pragma unroll
;               for (int jj = 0; jj < 4; ++jj) {
;                 const float sg = sigmoidf_(bias[nt] + acc[nt][jj]);
;                 stepbuf[0 * SV + (th * 16 + fq * 4 + jj) * 64 + nt * 16 + fr] = __expf(-0.6065306597126334f * sg);
;               }
;             __builtin_amdgcn_wave_barrier();
;             {
;               float wl[16];
; #pragma unroll
;               for (int i = 0; i < 16; ++i) wl[i] = stepbuf[0 * SV + (th * 16 + i) * 64 + lane];
;               float pr = 1.f;
; #pragma unroll
;               for (int i = 0; i < 16; ++i) { pr *= wl[i]; stepbuf[0 * SV + (th * 16 + i) * 64 + lane] = pr; }
;             }
;           } else {
; #pragma unroll
;             for (int nt = 0; nt < 4; ++nt)
; #pragma unroll
;               for (int jj = 0; jj < 4; ++jj) stepbuf[4 * SV + (th * 16 + fq * 4 + jj) * 64 + nt * 16 + fr] = sigmoidf_(bias[nt] + acc[nt][jj]);
.LBB0_573:
	s_andn2_b64 vcc, exec, s[40:41]
	s_cbranch_vccnz .LBB0_578
	s_mov_b64 s[40:41], -1
	s_and_b64 vcc, exec, s[6:7]
	s_waitcnt vmcnt(0)
	v_mfma_f32_16x16x32_bf16 v[56:59], v[12:15], v[220:223], 0
	v_mfma_f32_16x16x32_bf16 v[56:59], v[16:19], v[224:227], v[56:59]
	v_mfma_f32_16x16x32_bf16 v[60:63], v[12:15], v[228:231], 0
	v_mfma_f32_16x16x32_bf16 v[64:67], v[12:15], v[236:239], 0
	v_mfma_f32_16x16x32_bf16 v[68:71], v[12:15], v[244:247], 0
	v_mfma_f32_16x16x32_bf16 v[60:63], v[16:19], v[232:235], v[60:63]
	v_mfma_f32_16x16x32_bf16 v[94:97], v[16:19], v[240:243], v[64:67]
	v_mfma_f32_16x16x32_bf16 v[98:101], v[16:19], v[248:251], v[68:71]
	s_nop 7
	s_nop 3
	v_add_f32_e32 v56, v73, v56
	v_mul_f32_e32 v56, 0xbfb8aa3b, v56
	v_exp_f32_e32 v56, v56
	s_nop 1
	v_add_f32_e32 v56, 1.0, v56
	v_rcp_f32_e32 v66, v56
	s_nop 1
	v_add_f32_e32 v71, v73, v57
	v_add_f32_e32 v70, v73, v58
	v_add_f32_e32 v69, v73, v59
	v_add_f32_e32 v68, v110, v60
	v_add_f32_e32 v67, v110, v61
	v_add_f32_e32 v65, v110, v62
	v_add_f32_e32 v64, v110, v63
	v_add_f32_e32 v63, v111, v94
	v_add_f32_e32 v62, v111, v95
	v_add_f32_e32 v61, v111, v96
	v_add_f32_e32 v60, v111, v97
	v_add_f32_e32 v59, v112, v98
	v_add_f32_e32 v58, v112, v99
	v_add_f32_e32 v57, v112, v100
	v_add_f32_e32 v56, v112, v101
	s_cbranch_vccnz .LBB0_576
	v_mul_f32_e32 v96, 0xbfb8aa3b, v68
	v_exp_f32_e32 v96, v96
	v_add_u32_e32 v97, 0x8000, v185
	v_mul_f32_e32 v78, 0xbfb8aa3b, v71
	v_exp_f32_e32 v78, v78
	v_add_f32_e32 v96, 1.0, v96
	v_rcp_f32_e32 v96, v96
	v_add_u32_e32 v98, 0x8000, v186
	v_add_f32_e32 v78, 1.0, v78
	v_rcp_f32_e32 v78, v78
	ds_write2_b32 v97, v66, v96 offset1:16
	v_mul_f32_e32 v96, 0xbfb8aa3b, v67
	v_exp_f32_e32 v96, v96
	v_mul_f32_e32 v94, 0xbfb8aa3b, v70
	v_exp_f32_e32 v94, v94
	v_mul_f32_e32 v95, 0xbfb8aa3b, v69
	v_add_f32_e32 v96, 1.0, v96
	v_rcp_f32_e32 v96, v96
	v_add_f32_e32 v94, 1.0, v94
	v_rcp_f32_e32 v94, v94
	v_exp_f32_e32 v95, v95
	ds_write2_b32 v98, v78, v96 offset1:16
	v_mul_f32_e32 v78, 0xbfb8aa3b, v65
	v_exp_f32_e32 v78, v78
	v_add_u32_e32 v96, 0x8000, v187
	v_add_f32_e32 v95, 1.0, v95
	v_rcp_f32_e32 v95, v95
	v_add_f32_e32 v78, 1.0, v78
	v_rcp_f32_e32 v78, v78
	v_mul_f32_e32 v101, 0xbfb8aa3b, v59
	v_exp_f32_e32 v101, v101
	v_mul_f32_e32 v99, 0xbfb8aa3b, v61
	ds_write2_b32 v96, v94, v78 offset1:16
	v_mul_f32_e32 v78, 0xbfb8aa3b, v64
	v_exp_f32_e32 v78, v78
	v_add_u32_e32 v94, 0x8000, v188
	v_add_f32_e32 v101, 1.0, v101
	v_rcp_f32_e32 v101, v101
	v_add_f32_e32 v78, 1.0, v78
	v_rcp_f32_e32 v78, v78
	v_exp_f32_e32 v99, v99
	v_mul_f32_e32 v100, 0xbfb8aa3b, v60
	v_exp_f32_e32 v100, v100
	ds_write2_b32 v94, v95, v78 offset1:16
	v_mul_f32_e32 v78, 0xbfb8aa3b, v63
	v_exp_f32_e32 v78, v78
	v_mul_f32_e32 v95, 0xbfb8aa3b, v62
	v_exp_f32_e32 v95, v95
	v_add_f32_e32 v99, 1.0, v99
	v_add_f32_e32 v78, 1.0, v78
	v_rcp_f32_e32 v78, v78
	v_add_f32_e32 v95, 1.0, v95
	v_rcp_f32_e32 v95, v95
	v_rcp_f32_e32 v99, v99
	ds_write2_b32 v97, v78, v101 offset0:32 offset1:48
	v_mul_f32_e32 v78, 0xbfb8aa3b, v58
	v_exp_f32_e32 v78, v78
	v_add_f32_e32 v100, 1.0, v100
	v_rcp_f32_e32 v100, v100
	s_mov_b64 s[40:41], 0
	v_add_f32_e32 v78, 1.0, v78
	v_rcp_f32_e32 v78, v78
	ds_write2_b32 v98, v95, v78 offset0:32 offset1:48
	v_mul_f32_e32 v78, 0xbfb8aa3b, v57
	v_exp_f32_e32 v78, v78
	s_nop 0
	v_add_f32_e32 v78, 1.0, v78
	v_rcp_f32_e32 v78, v78
	ds_write2_b32 v96, v99, v78 offset0:32 offset1:48
	v_mul_f32_e32 v78, 0xbfb8aa3b, v56
	v_exp_f32_e32 v78, v78
	s_nop 0
	v_add_f32_e32 v78, 1.0, v78
	v_rcp_f32_e32 v78, v78
	ds_write2_b32 v94, v100, v78 offset0:32 offset1:48
